# v77 + softmax control flow: alpha==1 copy of the exp block goes straight to staging, the two wave-uniform tests issued back to back
# baseline (speedup 1.0000x reference)
; __device__ __forceinline__ bool softmax_pp(f32x16& p0, f32x16& p1, float& m_reg, float& l_reg, f32x16& negm, float& alpha, float& m_run, float dq, float nslope,
;                                            bf16x8& pa0, bf16x8& pa1, bf16x8& pa2, bf16x8& pa3) {
;     ...
;   float a = fmaxf(fmaxf(p0[0], p0[1]), p1[0]), bq = fmaxf(fmaxf(p0[2], p0[3]), p1[1]); a = fmaxf(fmaxf(a, p1[2]), p1[3]);
; #pragma unroll
;   for (int r = 4; r < 16; r += 4) { a = fmaxf(fmaxf(a, p0[r]), p0[r + 1]); bq = fmaxf(fmaxf(bq, p0[r + 2]), p0[r + 3]); a = fmaxf(fmaxf(a, p1[r]), p1[r + 1]); bq = fmaxf(fmaxf(bq, p1[r + 2]), p1[r + 3]); }
;   float pmax = fmaxf(a, bq);
;   { auto rr = __builtin_amdgcn_permlane32_swap(__float_as_uint(pmax), __float_as_uint(pmax), false, false);
;     pmax = fmaxf(__uint_as_float(rr[0]), __uint_as_float(rr[1])); }
;   alpha = 1.f;
;   { const float tmax = pmax + m_reg;
;     if (__all(tmax < m_run - TSKIP)) return false;
;     m_run = fmaxf(m_run, tmax); }
;   if (__builtin_expect(!__all(pmax <= THRL), 0)) { const float dl = fmaxf(pmax, 0.f); m_reg += dl; alpha = __builtin_amdgcn_exp2f(-dl);
; #pragma unroll
;     for (int r = 0; r < 16; ++r) { p0[r] -= dl; p1[r] -= dl; }
; #pragma unroll
;     for (int r = 0; r < 16; ++r) negm[r] = -m_reg; }
; #pragma unroll
;   for (int r = 0; r < 16; ++r) { p0[r] = __builtin_amdgcn_exp2f(p0[r]); p1[r] = __builtin_amdgcn_exp2f(p1[r]); }
;   float ps = 0;
; #pragma unroll
;   for (int r = 0; r < 16; ++r) ps += p0[r];
; #pragma unroll
;   for (int r = 0; r < 16; ++r) ps += p1[r];
;   { auto rr = __builtin_amdgcn_permlane32_swap(__float_as_uint(ps), __float_as_uint(ps), false, false);
;     ps = __uint_as_float(rr[0]) + __uint_as_float(rr[1]); }
;   l_reg = l_reg * alpha + ps;
;     ...
;   PK4(p0, 0, pa0); PK4(p0, 8, pa1); PK4(p1, 0, pa2); PK4(p1, 8, pa3);
.Lafter_bias_0:
	v_max_f32_e32 v0, v98, v99
	v_max3_f32 v14, v100, v101, v115
	v_max3_f32 v0, v0, v114, v116
	v_max3_f32 v0, v0, v117, v102
	v_max3_f32 v14, v14, v104, v105
	v_max3_f32 v0, v0, v103, v118
	v_max3_f32 v14, v14, v120, v121
	v_max3_f32 v0, v0, v119, v106
	v_max3_f32 v14, v14, v108, v109
	v_max3_f32 v0, v0, v107, v122
	v_max3_f32 v14, v14, v124, v125
	v_max3_f32 v0, v0, v123, v110
	v_max3_f32 v14, v14, v112, v113
	v_max3_f32 v0, v0, v111, v126
	v_max3_f32 v14, v14, v128, v129
	v_max3_f32 v0, v0, v127, v14
	v_mov_b32_e32 v14, v0
	s_nop 1
	v_permlane32_swap_b32_e32 v0, v14
	v_max_f32_e32 v167, v0, v14
	v_add_f32_e32 v14, v172, v166
	v_add_f32_e32 v15, v173, v167
	v_cmp_lt_f32_e32 vcc, v15, v14
	v_cmp_ge_f32_e64 s[16:17], s59, v167
	s_cmp_lg_u64 vcc, exec
	s_cselect_b64 s[14:15], -1, 0
	s_cmp_eq_u64 vcc, exec
	s_cbranch_scc1 .LBB0_375
	s_cmp_eq_u64 s[16:17], exec
	s_cbranch_scc0 .LBB0_395
.Lsf_common_0:
	v_max_f32_e32 v172, v172, v15
	v_exp_f32_e32 v2, v98
	v_exp_f32_e32 v3, v99
	v_exp_f32_e32 v4, v100
	v_exp_f32_e32 v5, v101
	v_exp_f32_e32 v12, v116
	v_exp_f32_e32 v6, v102
	v_exp_f32_e32 v7, v103
	v_add_f32_e32 v116, v3, v2
	v_exp_f32_e32 v8, v104
	v_add_f32_e32 v116, v4, v116
	v_exp_f32_e32 v9, v105
	v_add_f32_e32 v116, v5, v116
	v_exp_f32_e32 v100, v106
	v_add_f32_e32 v116, v6, v116
	v_exp_f32_e32 v102, v107
	v_add_f32_e32 v116, v7, v116
	v_exp_f32_e32 v104, v108
	v_add_f32_e32 v116, v8, v116
	v_exp_f32_e32 v106, v109
	v_add_f32_e32 v116, v9, v116
	v_exp_f32_e32 v108, v110
	v_add_f32_e32 v116, v100, v116
	v_exp_f32_e32 v110, v111
	v_add_f32_e32 v116, v102, v116
	v_exp_f32_e32 v112, v112
	v_add_f32_e32 v116, v104, v116
	v_exp_f32_e32 v113, v113
	v_add_f32_e32 v116, v106, v116
	v_exp_f32_e32 v10, v114
	v_add_f32_e32 v116, v108, v116
	v_exp_f32_e32 v11, v115
	v_add_f32_e32 v116, v110, v116
	v_add_f32_e32 v116, v112, v116
	v_exp_f32_e32 v13, v117
	v_add_f32_e32 v116, v113, v116
	v_exp_f32_e32 v14, v118
	v_add_f32_e32 v116, v10, v116
	v_exp_f32_e32 v15, v119
	v_add_f32_e32 v116, v11, v116
	v_exp_f32_e32 v98, v120
	v_add_f32_e32 v116, v12, v116
	v_exp_f32_e32 v99, v121
	v_add_f32_e32 v116, v13, v116
	v_exp_f32_e32 v101, v122
	v_add_f32_e32 v116, v14, v116
	v_exp_f32_e32 v103, v123
	v_add_f32_e32 v116, v15, v116
	v_exp_f32_e32 v105, v124
	v_add_f32_e32 v116, v98, v116
	v_exp_f32_e32 v107, v125
	v_add_f32_e32 v116, v99, v116
	v_exp_f32_e32 v109, v126
	v_add_f32_e32 v116, v101, v116
	v_exp_f32_e32 v111, v127
	v_add_f32_e32 v116, v103, v116
	v_exp_f32_e32 v114, v128
	v_add_f32_e32 v116, v105, v116
	v_exp_f32_e32 v115, v129
	v_add_f32_e32 v116, v107, v116
	v_add_f32_e32 v116, v109, v116
	v_add_f32_e32 v116, v111, v116
	v_add_f32_e32 v116, v114, v116
	v_add_f32_e32 v116, v115, v116
	v_mov_b32_e32 v117, v116
	s_nop 1
	v_permlane32_swap_b32_e32 v116, v117
	v_add_f32_e32 v116, v116, v117
	v_cvt_pk_bf16_f32 v2, v2, v3
	v_cvt_pk_bf16_f32 v3, v4, v5
	v_cvt_pk_bf16_f32 v4, v6, v7
	v_cvt_pk_bf16_f32 v5, v8, v9
	v_cvt_pk_bf16_f32 v6, v100, v102
	v_cvt_pk_bf16_f32 v7, v104, v106
	v_cvt_pk_bf16_f32 v8, v108, v110
	v_cvt_pk_bf16_f32 v9, v112, v113
	v_cvt_pk_bf16_f32 v10, v10, v11
	v_cvt_pk_bf16_f32 v11, v12, v13
	v_cvt_pk_bf16_f32 v12, v14, v15
	v_cvt_pk_bf16_f32 v13, v98, v99
	v_cvt_pk_bf16_f32 v162, v101, v103
	v_cvt_pk_bf16_f32 v163, v105, v107
	v_cvt_pk_bf16_f32 v164, v109, v111
	v_cvt_pk_bf16_f32 v165, v114, v115
	v_add_f32_e32 v80, v80, v116
	s_branch .LBB0_375
